# Up, QK and Vt GEMMs: first K iteration peeled so each accumulator's first MFMA takes the inline constant 0 as srcC; the 128-move zero fill in the unit-loop header is gone
# speedup vs baseline: 1.0192x; 1.0041x over previous
; #define PG8_STAGE(bufoff, gbase, voff) do { _Pragma("unroll") for (int _i = 0; _i < 2; ++_i) \
;         __builtin_amdgcn_global_load_lds((const unsigned*)((const char*)(gbase) + (voff)[_i]), (LAS unsigned*)(lds + (bufoff) + ldsw + _i * 8192), 16, 0, 0); } while (0)
; #define PG8_LDA(dst, b, h) do { _Pragma("unroll") for (int m = 0; m < 4; ++m) _Pragma("unroll") for (int k = 0; k < 2; ++k) dst[m][k] = *(const LAS bf16x8*)(lds + PG8_SA(b, h) + aoff + m * 2048 + k * 1024); } while (0)
; #define PG8_LDB(dst, b, h) do { _Pragma("unroll") for (int n = 0; n < 2; ++n) _Pragma("unroll") for (int k = 0; k < 2; ++k) dst[n][k] = *(const LAS bf16x8*)(lds + PG8_SB(b, h) + boff + n * 2048 + k * 1024); } while (0)
; #define PG8_WAIT_V(n) asm volatile("s_waitcnt vmcnt(" #n ")" ::: "memory")
; #define PG8_WAIT_L(n) asm volatile("s_waitcnt lgkmcnt(" #n ")" ::: "memory")
; #define PG8_BAR __builtin_amdgcn_s_barrier()
; template <class Epi, class Sched>
; __device__ __forceinline__ void gemm_phase(LAS unsigned char* lds, const Gemm g, const Sched& S, const Epi& E) {
;     ...
;     for (;;) {
;         const bool has_next = S.next(ui + 1, nxt);
;         const char* nA = has_next ? (const char*)g.A + (size_t)nxt.pm * tstepA + (size_t)nxt.pn * g.a_pn_off * 2 : cA; const char* nB = has_next ? (const char*)g.Bt + (size_t)nxt.pn * tstepB : cB;
;         for (int t = 0; t < nt; t += 2) {
;             const bool last = (t == nt - 2);
;             const char* a1 = cA + (size_t)(t + 1) * kstep;
;             const char* a2 = last ? nA : cA + (size_t)(t + 2) * kstep; const char* b2 = last ? nB : cB + (size_t)(t + 2) * kstep;
;             const char* a3 = a2 + kstep; const char* b3 = b2 + kstep;
;             PG8_LDB(B0, 0, 0); PG8_LDB(B1, 0, 1); PG8_SCHED; PG8_LDA(At, 0, 0); PG8_STAGE(PG8_SA(1, 1), a1 + hstepA, voffA);
;             PG8_WAIT_V(8); PG8_WAIT_L(0); PG8_BAR; PG8_MMA(0, 0, At, B0); PG8_MMA(0, 1, At, B1); PG8_BAR; PG8_SCHED;
;             PG8_LDA(At, 0, 1); PG8_STAGE(PG8_SB(0, 0), b2, voffB); PG8_STAGE(PG8_SB(0, 1), b2 + hstepB, voffB); PG8_STAGE(PG8_SA(0, 0), a2, voffA);
;             PG8_WAIT_V(8); PG8_WAIT_L(0); PG8_BAR; PG8_MMA(1, 0, At, B0); PG8_MMA(1, 1, At, B1); PG8_BAR; PG8_SCHED;
; __device__ __forceinline__ void acc_zero(f32x4 (&acc)[2][2][4][2]) {
;     ...
;                 for (int n = 0; n < 2; ++n) acc[a][b][m][n] = (f32x4){0.f, 0.f, 0.f, 0.f};
.LBB0_231:
	s_ashr_i32 s83, s82, 31
	s_lshl_b64 s[36:37], s[82:83], 19
	s_add_u32 s84, s4, s36
	s_addc_u32 s85, s5, s37
	s_and_b64 s[36:37], s[70:71], exec
	s_cselect_b32 s43, s85, s19
	s_cselect_b32 s48, s84, s18
	s_ashr_i32 s81, s80, 31
	s_lshl_b64 s[36:37], s[80:81], 19
	v_readlane_b32 s12, v248, 5
	s_add_u32 s36, s12, s36
	v_readlane_b32 s12, v248, 6
	s_addc_u32 s37, s12, s37
	s_and_b64 s[86:87], s[70:71], exec
	s_cselect_b32 s49, s37, s21
	s_cselect_b32 s53, s36, s20
	s_add_u32 s18, s18, 0x40080
	s_addc_u32 s19, s19, 0
	s_add_u32 s54, s20, 0x100
	s_addc_u32 s81, s21, 0
	s_mov_b32 s83, -2
	s_add_u32 s20, s18, 0xfffc0080
	s_addc_u32 s21, s19, -1
	s_add_i32 s88, 0, 0x10000
	s_cmp_eq_u32 s83, 12
	s_cselect_b32 s21, s43, s21
	s_cselect_b32 s20, s48, s20
	s_cselect_b32 s87, s49, s81
	s_cselect_b32 s86, s53, s54
	s_add_i32 s90, 0, 0x14000
	s_add_u32 s100, s20, 0x80
	s_addc_u32 s101, s21, 0
	ds_read_b128 v[130:133], v246
	ds_read_b128 v[134:137], v246 offset:1024
	ds_read_b128 v[138:141], v246 offset:2048
	ds_read_b128 v[142:145], v246 offset:3072
	ds_read_b128 v[146:149], v246 offset:16384
	ds_read_b128 v[150:153], v246 offset:17408
	ds_read_b128 v[154:157], v246 offset:18432
	ds_read_b128 v[158:161], v246 offset:19456
	s_add_i32 m0, s9, 0xc000
	ds_read_b128 v[162:165], v222
	ds_read_b128 v[166:169], v222 offset:1024
	ds_read_b128 v[194:197], v222 offset:2048
	ds_read_b128 v[198:201], v222 offset:3072
	ds_read_b128 v[202:205], v222 offset:4096
	ds_read_b128 v[224:227], v222 offset:5120
	ds_read_b128 v[228:231], v222 offset:6144
	ds_read_b128 v[232:235], v222 offset:7168
	global_load_lds_dwordx4 v170, s[18:19]
	s_add_i32 m0, s9, 0xe000
	s_nop 0
	global_load_lds_dwordx4 v190, s[18:19]
	s_waitcnt vmcnt(8)
	s_waitcnt lgkmcnt(0)
	s_barrier
	s_setprio 1
	s_waitcnt lgkmcnt(0)
	v_mfma_f32_16x16x32_bf16 v[126:129], v[130:133], v[162:165], 0
	v_mfma_f32_16x16x32_bf16 v[118:121], v[138:141], v[162:165], 0
	v_mfma_f32_16x16x32_bf16 v[110:113], v[130:133], v[194:197], 0
	v_mfma_f32_16x16x32_bf16 v[102:105], v[138:141], v[194:197], 0
	v_mfma_f32_16x16x32_bf16 v[94:97], v[130:133], v[202:205], 0
	v_mfma_f32_16x16x32_bf16 v[86:89], v[138:141], v[202:205], 0
	v_mfma_f32_16x16x32_bf16 v[78:81], v[130:133], v[228:231], 0
	v_mfma_f32_16x16x32_bf16 v[70:73], v[138:141], v[228:231], 0
	v_mfma_f32_16x16x32_bf16 v[126:129], v[134:137], v[166:169], v[126:129]
	v_mfma_f32_16x16x32_bf16 v[118:121], v[142:145], v[166:169], v[118:121]
	v_mfma_f32_16x16x32_bf16 v[110:113], v[134:137], v[198:201], v[110:113]
	v_mfma_f32_16x16x32_bf16 v[102:105], v[142:145], v[198:201], v[102:105]
	v_mfma_f32_16x16x32_bf16 v[94:97], v[134:137], v[224:227], v[94:97]
	v_mfma_f32_16x16x32_bf16 v[86:89], v[142:145], v[224:227], v[86:89]
	v_mfma_f32_16x16x32_bf16 v[78:81], v[134:137], v[232:235], v[78:81]
	v_mfma_f32_16x16x32_bf16 v[70:73], v[142:145], v[232:235], v[70:73]
	s_setprio 0
	s_setprio 1
	v_mfma_f32_16x16x32_bf16 v[122:125], v[146:149], v[162:165], 0
	v_mfma_f32_16x16x32_bf16 v[114:117], v[154:157], v[162:165], 0
	v_mfma_f32_16x16x32_bf16 v[106:109], v[146:149], v[194:197], 0
	v_mfma_f32_16x16x32_bf16 v[98:101], v[154:157], v[194:197], 0
	v_mfma_f32_16x16x32_bf16 v[90:93], v[146:149], v[202:205], 0
	v_mfma_f32_16x16x32_bf16 v[82:85], v[154:157], v[202:205], 0
	v_mfma_f32_16x16x32_bf16 v[74:77], v[146:149], v[228:231], 0
	v_mfma_f32_16x16x32_bf16 v[66:69], v[154:157], v[228:231], 0
	v_mfma_f32_16x16x32_bf16 v[122:125], v[150:153], v[166:169], v[122:125]
	v_mfma_f32_16x16x32_bf16 v[114:117], v[158:161], v[166:169], v[114:117]
	v_mfma_f32_16x16x32_bf16 v[106:109], v[150:153], v[198:201], v[106:109]
	v_mfma_f32_16x16x32_bf16 v[98:101], v[158:161], v[198:201], v[98:101]
	v_mfma_f32_16x16x32_bf16 v[90:93], v[150:153], v[224:227], v[90:93]
	v_mfma_f32_16x16x32_bf16 v[82:85], v[158:161], v[224:227], v[82:85]
	v_mfma_f32_16x16x32_bf16 v[74:77], v[150:153], v[232:235], v[74:77]
	v_mfma_f32_16x16x32_bf16 v[66:69], v[158:161], v[232:235], v[66:69]
	s_setprio 0
	s_barrier
	s_add_i32 s88, s88, s8
	s_mov_b32 m0, s88
	ds_read_b128 v[162:165], v222 offset:16384
	ds_read_b128 v[166:169], v222 offset:17408
	ds_read_b128 v[194:197], v222 offset:18432
	ds_read_b128 v[198:201], v222 offset:19456
	ds_read_b128 v[202:205], v222 offset:20480
	ds_read_b128 v[224:227], v222 offset:21504
	ds_read_b128 v[228:231], v222 offset:22528
	ds_read_b128 v[232:235], v222 offset:23552
	global_load_lds_dwordx4 v172, s[86:87]
	s_add_i32 m0, s88, 0x2000
	s_add_u32 s88, s86, 0x40000
	s_addc_u32 s89, s87, 0
	s_add_i32 s90, s90, s8
	global_load_lds_dwordx4 v192, s[86:87]
	s_mov_b32 m0, s90
	s_nop 0
	global_load_lds_dwordx4 v172, s[88:89]
	s_add_i32 m0, s90, 0x2000
	s_nop 0
	global_load_lds_dwordx4 v192, s[88:89]
	s_mov_b32 m0, s9
	s_nop 0
	global_load_lds_dwordx4 v170, s[20:21]
	s_mov_b32 m0, s28
	s_nop 0
	global_load_lds_dwordx4 v190, s[20:21]
	s_waitcnt vmcnt(8)
	s_waitcnt lgkmcnt(0)
	s_barrier
; #define PG8_STAGE(bufoff, gbase, voff) do { _Pragma("unroll") for (int _i = 0; _i < 2; ++_i) \
;         __builtin_amdgcn_global_load_lds((const unsigned*)((const char*)(gbase) + (voff)[_i]), (LAS unsigned*)(lds + (bufoff) + ldsw + _i * 8192), 16, 0, 0); } while (0)
; #define PG8_LDA(dst, b, h) do { _Pragma("unroll") for (int m = 0; m < 4; ++m) _Pragma("unroll") for (int k = 0; k < 2; ++k) dst[m][k] = *(const LAS bf16x8*)(lds + PG8_SA(b, h) + aoff + m * 2048 + k * 1024); } while (0)
; #define PG8_LDB(dst, b, h) do { _Pragma("unroll") for (int n = 0; n < 2; ++n) _Pragma("unroll") for (int k = 0; k < 2; ++k) dst[n][k] = *(const LAS bf16x8*)(lds + PG8_SB(b, h) + boff + n * 2048 + k * 1024); } while (0)
; #define PG8_MMA(ai, bj, At, Bt) do { __builtin_amdgcn_s_setprio(1); _Pragma("unroll") for (int m = 0; m < 4; ++m) _Pragma("unroll") for (int n = 0; n < 2; ++n) _Pragma("unroll") for (int k = 0; k < 2; ++k) \
;         acc[ai][bj][m][n] = __builtin_amdgcn_mfma_f32_16x16x32_bf16(Bt[n][k], At[m][k], acc[ai][bj][m][n], 0, 0, 0); __builtin_amdgcn_s_setprio(0); } while (0)
; #define PG8_WAIT_V(n) asm volatile("s_waitcnt vmcnt(" #n ")" ::: "memory")
; #define PG8_WAIT_L(n) asm volatile("s_waitcnt lgkmcnt(" #n ")" ::: "memory")
; #define PG8_BAR __builtin_amdgcn_s_barrier()
; #define PG8_SCHED __builtin_amdgcn_sched_barrier(0)
; template <class Epi, class Sched>
; __device__ __forceinline__ void gemm_phase(LAS unsigned char* lds, const Gemm g, const Sched& S, const Epi& E) {
;     ...
;             PG8_WAIT_V(8); PG8_WAIT_L(0); PG8_BAR; PG8_MMA(1, 0, At, B0); PG8_MMA(1, 1, At, B1); PG8_BAR; PG8_SCHED;
;             PG8_LDB(B0, 1, 0); PG8_LDB(B1, 1, 1); PG8_SCHED; PG8_LDA(At, 1, 0); PG8_STAGE(PG8_SA(0, 1), a2 + hstepA, voffA);
;             PG8_WAIT_V(8); PG8_WAIT_L(0); PG8_BAR; PG8_MMA(0, 0, At, B0); PG8_MMA(0, 1, At, B1); PG8_BAR; PG8_SCHED;
	s_setprio 1
	s_waitcnt lgkmcnt(0)
	v_mfma_f32_16x16x32_bf16 v[62:65], v[130:133], v[162:165], 0
	v_mfma_f32_16x16x32_bf16 v[54:57], v[138:141], v[162:165], 0
	v_mfma_f32_16x16x32_bf16 v[46:49], v[130:133], v[194:197], 0
	v_mfma_f32_16x16x32_bf16 v[38:41], v[138:141], v[194:197], 0
	v_mfma_f32_16x16x32_bf16 v[30:33], v[130:133], v[202:205], 0
	v_mfma_f32_16x16x32_bf16 v[22:25], v[138:141], v[202:205], 0
	v_mfma_f32_16x16x32_bf16 v[14:17], v[130:133], v[228:231], 0
	v_mfma_f32_16x16x32_bf16 v[6:9], v[138:141], v[228:231], 0
	v_mfma_f32_16x16x32_bf16 v[62:65], v[134:137], v[166:169], v[62:65]
	v_mfma_f32_16x16x32_bf16 v[54:57], v[142:145], v[166:169], v[54:57]
	v_mfma_f32_16x16x32_bf16 v[46:49], v[134:137], v[198:201], v[46:49]
	v_mfma_f32_16x16x32_bf16 v[38:41], v[142:145], v[198:201], v[38:41]
	v_mfma_f32_16x16x32_bf16 v[30:33], v[134:137], v[224:227], v[30:33]
	v_mfma_f32_16x16x32_bf16 v[22:25], v[142:145], v[224:227], v[22:25]
	v_mfma_f32_16x16x32_bf16 v[14:17], v[134:137], v[232:235], v[14:17]
	v_mfma_f32_16x16x32_bf16 v[6:9], v[142:145], v[232:235], v[6:9]
	s_setprio 0
	s_setprio 1
	v_mfma_f32_16x16x32_bf16 v[58:61], v[146:149], v[162:165], 0
	v_mfma_f32_16x16x32_bf16 v[50:53], v[154:157], v[162:165], 0
	v_mfma_f32_16x16x32_bf16 v[42:45], v[146:149], v[194:197], 0
	v_mfma_f32_16x16x32_bf16 v[34:37], v[154:157], v[194:197], 0
	v_mfma_f32_16x16x32_bf16 v[26:29], v[146:149], v[202:205], 0
	v_mfma_f32_16x16x32_bf16 v[18:21], v[154:157], v[202:205], 0
	v_mfma_f32_16x16x32_bf16 v[10:13], v[146:149], v[228:231], 0
	v_mfma_f32_16x16x32_bf16 v[2:5], v[154:157], v[228:231], 0
	v_mfma_f32_16x16x32_bf16 v[58:61], v[150:153], v[166:169], v[58:61]
	v_mfma_f32_16x16x32_bf16 v[50:53], v[158:161], v[166:169], v[50:53]
	v_mfma_f32_16x16x32_bf16 v[42:45], v[150:153], v[198:201], v[42:45]
	v_mfma_f32_16x16x32_bf16 v[34:37], v[158:161], v[198:201], v[34:37]
	v_mfma_f32_16x16x32_bf16 v[26:29], v[150:153], v[224:227], v[26:29]
	v_mfma_f32_16x16x32_bf16 v[18:21], v[158:161], v[224:227], v[18:21]
	v_mfma_f32_16x16x32_bf16 v[10:13], v[150:153], v[232:235], v[10:13]
	v_mfma_f32_16x16x32_bf16 v[2:5], v[158:161], v[232:235], v[2:5]
	s_setprio 0
	s_barrier
	s_add_i32 s88, 0, 0x18000
	s_add_i32 s89, 0, 0x1c000
	ds_read_b128 v[130:133], v246 offset:32768
	ds_read_b128 v[134:137], v246 offset:33792
	ds_read_b128 v[138:141], v246 offset:34816
	ds_read_b128 v[142:145], v246 offset:35840
	ds_read_b128 v[146:149], v246 offset:49152
	ds_read_b128 v[150:153], v246 offset:50176
	ds_read_b128 v[154:157], v246 offset:51200
	ds_read_b128 v[158:161], v246 offset:52224
	s_add_u32 s20, s20, 0x40000
	s_addc_u32 s21, s21, 0
	s_mov_b32 m0, s29
	ds_read_b128 v[162:165], v222 offset:32768
	ds_read_b128 v[166:169], v222 offset:33792
	ds_read_b128 v[194:197], v222 offset:34816
	ds_read_b128 v[198:201], v222 offset:35840
	ds_read_b128 v[202:205], v222 offset:36864
	ds_read_b128 v[224:227], v222 offset:37888
	ds_read_b128 v[228:231], v222 offset:38912
	ds_read_b128 v[232:235], v222 offset:39936
	global_load_lds_dwordx4 v170, s[20:21]
	s_mov_b32 m0, s30
	s_nop 0
	global_load_lds_dwordx4 v190, s[20:21]
	s_waitcnt vmcnt(8)
	s_waitcnt lgkmcnt(0)
	s_barrier
	s_setprio 1
	s_waitcnt lgkmcnt(0)
	v_mfma_f32_16x16x32_bf16 v[126:129], v[130:133], v[162:165], v[126:129]
	v_mfma_f32_16x16x32_bf16 v[118:121], v[138:141], v[162:165], v[118:121]
	v_mfma_f32_16x16x32_bf16 v[110:113], v[130:133], v[194:197], v[110:113]
	v_mfma_f32_16x16x32_bf16 v[102:105], v[138:141], v[194:197], v[102:105]
	v_mfma_f32_16x16x32_bf16 v[94:97], v[130:133], v[202:205], v[94:97]
	v_mfma_f32_16x16x32_bf16 v[86:89], v[138:141], v[202:205], v[86:89]
	v_mfma_f32_16x16x32_bf16 v[78:81], v[130:133], v[228:231], v[78:81]
	v_mfma_f32_16x16x32_bf16 v[70:73], v[138:141], v[228:231], v[70:73]
	v_mfma_f32_16x16x32_bf16 v[126:129], v[134:137], v[166:169], v[126:129]
	v_mfma_f32_16x16x32_bf16 v[118:121], v[142:145], v[166:169], v[118:121]
	v_mfma_f32_16x16x32_bf16 v[110:113], v[134:137], v[198:201], v[110:113]
	v_mfma_f32_16x16x32_bf16 v[102:105], v[142:145], v[198:201], v[102:105]
	v_mfma_f32_16x16x32_bf16 v[94:97], v[134:137], v[224:227], v[94:97]
	v_mfma_f32_16x16x32_bf16 v[86:89], v[142:145], v[224:227], v[86:89]
	v_mfma_f32_16x16x32_bf16 v[78:81], v[134:137], v[232:235], v[78:81]
	v_mfma_f32_16x16x32_bf16 v[70:73], v[142:145], v[232:235], v[70:73]
	s_setprio 0
	s_setprio 1
	v_mfma_f32_16x16x32_bf16 v[122:125], v[146:149], v[162:165], v[122:125]
	v_mfma_f32_16x16x32_bf16 v[114:117], v[154:157], v[162:165], v[114:117]
	v_mfma_f32_16x16x32_bf16 v[106:109], v[146:149], v[194:197], v[106:109]
	v_mfma_f32_16x16x32_bf16 v[98:101], v[154:157], v[194:197], v[98:101]
	v_mfma_f32_16x16x32_bf16 v[90:93], v[146:149], v[202:205], v[90:93]
	v_mfma_f32_16x16x32_bf16 v[82:85], v[154:157], v[202:205], v[82:85]
	v_mfma_f32_16x16x32_bf16 v[74:77], v[146:149], v[228:231], v[74:77]
	v_mfma_f32_16x16x32_bf16 v[66:69], v[154:157], v[228:231], v[66:69]
	v_mfma_f32_16x16x32_bf16 v[122:125], v[150:153], v[166:169], v[122:125]
	v_mfma_f32_16x16x32_bf16 v[114:117], v[158:161], v[166:169], v[114:117]
	v_mfma_f32_16x16x32_bf16 v[106:109], v[150:153], v[198:201], v[106:109]
	v_mfma_f32_16x16x32_bf16 v[98:101], v[158:161], v[198:201], v[98:101]
	v_mfma_f32_16x16x32_bf16 v[90:93], v[150:153], v[224:227], v[90:93]
	v_mfma_f32_16x16x32_bf16 v[82:85], v[158:161], v[224:227], v[82:85]
	v_mfma_f32_16x16x32_bf16 v[74:77], v[150:153], v[232:235], v[74:77]
	v_mfma_f32_16x16x32_bf16 v[66:69], v[158:161], v[232:235], v[66:69]
	s_setprio 0
	s_barrier
; #define PG8_STAGE(bufoff, gbase, voff) do { _Pragma("unroll") for (int _i = 0; _i < 2; ++_i) \
;         __builtin_amdgcn_global_load_lds((const unsigned*)((const char*)(gbase) + (voff)[_i]), (LAS unsigned*)(lds + (bufoff) + ldsw + _i * 8192), 16, 0, 0); } while (0)
; #define PG8_LDA(dst, b, h) do { _Pragma("unroll") for (int m = 0; m < 4; ++m) _Pragma("unroll") for (int k = 0; k < 2; ++k) dst[m][k] = *(const LAS bf16x8*)(lds + PG8_SA(b, h) + aoff + m * 2048 + k * 1024); } while (0)
; #define PG8_MMA(ai, bj, At, Bt) do { __builtin_amdgcn_s_setprio(1); _Pragma("unroll") for (int m = 0; m < 4; ++m) _Pragma("unroll") for (int n = 0; n < 2; ++n) _Pragma("unroll") for (int k = 0; k < 2; ++k) \
;         acc[ai][bj][m][n] = __builtin_amdgcn_mfma_f32_16x16x32_bf16(Bt[n][k], At[m][k], acc[ai][bj][m][n], 0, 0, 0); __builtin_amdgcn_s_setprio(0); } while (0)
; #define PG8_WAIT_V(n) asm volatile("s_waitcnt vmcnt(" #n ")" ::: "memory")
; #define PG8_WAIT_L(n) asm volatile("s_waitcnt lgkmcnt(" #n ")" ::: "memory")
; #define PG8_BAR __builtin_amdgcn_s_barrier()
; #define PG8_SCHED __builtin_amdgcn_sched_barrier(0)
; template <class Epi, class Sched>
; __device__ __forceinline__ void gemm_phase(LAS unsigned char* lds, const Gemm g, const Sched& S, const Epi& E) {
;     ...
;             PG8_LDA(At, 1, 1); PG8_STAGE(PG8_SB(1, 0), b3, voffB); PG8_STAGE(PG8_SB(1, 1), b3 + hstepB, voffB); PG8_STAGE(PG8_SA(1, 0), a3, voffA);
;             PG8_WAIT_V(8); PG8_WAIT_L(0); PG8_BAR; PG8_MMA(1, 0, At, B0); PG8_MMA(1, 1, At, B1); PG8_BAR; PG8_SCHED;
;         }
	s_add_i32 s20, s8, 0x18000
	s_add_u32 s88, s86, 0x80
	s_addc_u32 s89, s87, 0
	s_mov_b32 m0, s20
	ds_read_b128 v[162:165], v222 offset:49152
	ds_read_b128 v[166:169], v222 offset:50176
	ds_read_b128 v[194:197], v222 offset:51200
	ds_read_b128 v[198:201], v222 offset:52224
	ds_read_b128 v[202:205], v222 offset:53248
	ds_read_b128 v[224:227], v222 offset:54272
	ds_read_b128 v[228:231], v222 offset:55296
	ds_read_b128 v[232:235], v222 offset:56320
	global_load_lds_dwordx4 v172, s[88:89]
	s_add_i32 m0, s20, 0x2000
	s_add_u32 s20, s86, 0x40080
	s_addc_u32 s21, s87, 0
	s_add_i32 s12, s8, 0x1c000
	global_load_lds_dwordx4 v192, s[88:89]
	s_mov_b32 m0, s12
	s_nop 0
	global_load_lds_dwordx4 v172, s[20:21]
	s_add_i32 m0, s12, 0x2000
	s_nop 0
	global_load_lds_dwordx4 v192, s[20:21]
	s_mov_b32 m0, s31
	s_nop 0
	global_load_lds_dwordx4 v170, s[100:101]
	s_mov_b32 m0, s34
	s_nop 0
	global_load_lds_dwordx4 v190, s[100:101]
	s_waitcnt vmcnt(8)
	s_waitcnt lgkmcnt(0)
	s_barrier
	s_setprio 1
	s_waitcnt lgkmcnt(0)
	v_mfma_f32_16x16x32_bf16 v[62:65], v[130:133], v[162:165], v[62:65]
	v_mfma_f32_16x16x32_bf16 v[54:57], v[138:141], v[162:165], v[54:57]
	v_mfma_f32_16x16x32_bf16 v[46:49], v[130:133], v[194:197], v[46:49]
	v_mfma_f32_16x16x32_bf16 v[38:41], v[138:141], v[194:197], v[38:41]
	v_mfma_f32_16x16x32_bf16 v[30:33], v[130:133], v[202:205], v[30:33]
	v_mfma_f32_16x16x32_bf16 v[22:25], v[138:141], v[202:205], v[22:25]
	v_mfma_f32_16x16x32_bf16 v[14:17], v[130:133], v[228:231], v[14:17]
	v_mfma_f32_16x16x32_bf16 v[6:9], v[138:141], v[228:231], v[6:9]
	v_mfma_f32_16x16x32_bf16 v[62:65], v[134:137], v[166:169], v[62:65]
	v_mfma_f32_16x16x32_bf16 v[54:57], v[142:145], v[166:169], v[54:57]
	v_mfma_f32_16x16x32_bf16 v[46:49], v[134:137], v[198:201], v[46:49]
	v_mfma_f32_16x16x32_bf16 v[38:41], v[142:145], v[198:201], v[38:41]
	v_mfma_f32_16x16x32_bf16 v[30:33], v[134:137], v[224:227], v[30:33]
	v_mfma_f32_16x16x32_bf16 v[22:25], v[142:145], v[224:227], v[22:25]
	v_mfma_f32_16x16x32_bf16 v[14:17], v[134:137], v[232:235], v[14:17]
	v_mfma_f32_16x16x32_bf16 v[6:9], v[142:145], v[232:235], v[6:9]
	s_setprio 0
	s_setprio 1
	v_mfma_f32_16x16x32_bf16 v[58:61], v[146:149], v[162:165], v[58:61]
	v_mfma_f32_16x16x32_bf16 v[50:53], v[154:157], v[162:165], v[50:53]
	v_mfma_f32_16x16x32_bf16 v[42:45], v[146:149], v[194:197], v[42:45]
	v_mfma_f32_16x16x32_bf16 v[34:37], v[154:157], v[194:197], v[34:37]
	v_mfma_f32_16x16x32_bf16 v[26:29], v[146:149], v[202:205], v[26:29]
	v_mfma_f32_16x16x32_bf16 v[18:21], v[154:157], v[202:205], v[18:21]
	v_mfma_f32_16x16x32_bf16 v[10:13], v[146:149], v[228:231], v[10:13]
	v_mfma_f32_16x16x32_bf16 v[2:5], v[154:157], v[228:231], v[2:5]
	v_mfma_f32_16x16x32_bf16 v[58:61], v[150:153], v[166:169], v[58:61]
	v_mfma_f32_16x16x32_bf16 v[50:53], v[158:161], v[166:169], v[50:53]
	v_mfma_f32_16x16x32_bf16 v[42:45], v[150:153], v[198:201], v[42:45]
	v_mfma_f32_16x16x32_bf16 v[34:37], v[158:161], v[198:201], v[34:37]
	v_mfma_f32_16x16x32_bf16 v[26:29], v[150:153], v[224:227], v[26:29]
	v_mfma_f32_16x16x32_bf16 v[18:21], v[158:161], v[224:227], v[18:21]
	v_mfma_f32_16x16x32_bf16 v[10:13], v[150:153], v[232:235], v[10:13]
	v_mfma_f32_16x16x32_bf16 v[2:5], v[158:161], v[232:235], v[2:5]
	s_setprio 0
	s_barrier
	s_add_i32 s83, s83, 2
	s_add_u32 s18, s18, 0x100
	s_addc_u32 s19, s19, 0
	s_add_u32 s54, s54, 0x100
	s_addc_u32 s81, s81, 0
	s_cmp_gt_u32 s83, 13

; #define PG8_STAGE(bufoff, gbase, voff) do { _Pragma("unroll") for (int _i = 0; _i < 2; ++_i) \
;         __builtin_amdgcn_global_load_lds((const unsigned*)((const char*)(gbase) + (voff)[_i]), (LAS unsigned*)(lds + (bufoff) + ldsw + _i * 8192), 16, 0, 0); } while (0)
; #define PG8_LDA(dst, b, h) do { _Pragma("unroll") for (int m = 0; m < 4; ++m) _Pragma("unroll") for (int k = 0; k < 2; ++k) dst[m][k] = *(const LAS bf16x8*)(lds + PG8_SA(b, h) + aoff + m * 2048 + k * 1024); } while (0)
; #define PG8_LDB(dst, b, h) do { _Pragma("unroll") for (int n = 0; n < 2; ++n) _Pragma("unroll") for (int k = 0; k < 2; ++k) dst[n][k] = *(const LAS bf16x8*)(lds + PG8_SB(b, h) + boff + n * 2048 + k * 1024); } while (0)
; #define PG8_MMA(ai, bj, At, Bt) do { __builtin_amdgcn_s_setprio(1); _Pragma("unroll") for (int m = 0; m < 4; ++m) _Pragma("unroll") for (int n = 0; n < 2; ++n) _Pragma("unroll") for (int k = 0; k < 2; ++k) \
;         acc[ai][bj][m][n] = __builtin_amdgcn_mfma_f32_16x16x32_bf16(Bt[n][k], At[m][k], acc[ai][bj][m][n], 0, 0, 0); __builtin_amdgcn_s_setprio(0); } while (0)
; #define PG8_WAIT_V(n) asm volatile("s_waitcnt vmcnt(" #n ")" ::: "memory")
; #define PG8_WAIT_L(n) asm volatile("s_waitcnt lgkmcnt(" #n ")" ::: "memory")
; template <class Epi, class Sched>
; __device__ __forceinline__ void gemm_phase(LAS unsigned char* lds, const Gemm g, const Sched& S, const Epi& E) {
;     ...
;         const bool has_next = S.next(ui + 1, nxt);
;         const char* nA = has_next ? (const char*)g.A + (size_t)nxt.pm * tstepA + (size_t)nxt.pn * g.a_pn_off * 2 : cA; const char* nB = has_next ? (const char*)g.Bt + (size_t)nxt.pn * tstepB : cB;
;         for (int t = 0; t < nt; t += 2) {
;             const bool last = (t == nt - 2);
;             const char* a1 = cA + (size_t)(t + 1) * kstep;
;             const char* a2 = last ? nA : cA + (size_t)(t + 2) * kstep; const char* b2 = last ? nB : cB + (size_t)(t + 2) * kstep;
;             const char* a3 = a2 + kstep; const char* b3 = b2 + kstep;
;             PG8_LDB(B0, 0, 0); PG8_LDB(B1, 0, 1); PG8_SCHED; PG8_LDA(At, 0, 0); PG8_STAGE(PG8_SA(1, 1), a1 + hstepA, voffA);
;             PG8_WAIT_V(8); PG8_WAIT_L(0); PG8_BAR; PG8_MMA(0, 0, At, B0); PG8_MMA(0, 1, At, B1); PG8_BAR; PG8_SCHED;
;             PG8_LDA(At, 0, 1); PG8_STAGE(PG8_SB(0, 0), b2, voffB); PG8_STAGE(PG8_SB(0, 1), b2 + hstepB, voffB); PG8_STAGE(PG8_SA(0, 0), a2, voffA);
.LBB0_348:
	s_ashr_i32 s71, s70, 31
	s_lshl_b64 s[48:49], s[70:71], 19
	s_add_u32 s72, s4, s48
	s_addc_u32 s73, s5, s49
	s_and_b64 s[48:49], s[66:67], exec
	s_cselect_b32 s48, s73, s19
	s_cselect_b32 s49, s72, s18
	s_ashr_i32 s69, s68, 31
	s_lshl_b64 s[74:75], s[68:69], 19
	v_readlane_b32 s12, v248, 13
	s_add_u32 s74, s12, s74
	v_readlane_b32 s12, v248, 14
	s_addc_u32 s75, s12, s75
	s_and_b64 s[76:77], s[66:67], exec
	s_cselect_b32 s53, s75, s21
	s_cselect_b32 s54, s74, s20
	s_add_u32 s18, s18, 0x40080
	s_addc_u32 s19, s19, 0
	s_add_u32 s69, s20, 0x100
	s_addc_u32 s71, s21, 0
	s_mov_b32 s78, -2
	s_waitcnt vmcnt(0)
	v_add_u32_e32 v255, 0x10000, v139
	s_add_u32 s20, s18, 0xfffc0080
	s_addc_u32 s21, s19, -1
	s_add_i32 s79, 0, 0x10000
	s_cmp_eq_u32 s78, 12
	s_cselect_b32 s21, s48, s21
	s_cselect_b32 s20, s49, s20
	s_cselect_b32 s77, s53, s71
	s_cselect_b32 s76, s54, s69
	s_add_u32 s100, s20, 0x80
	s_addc_u32 s101, s21, 0
	s_add_i32 s82, 0, 0x14000
	ds_read_b128 v[150:153], v255
	ds_read_b128 v[154:157], v255 offset:1024
	ds_read_b128 v[158:161], v255 offset:2048
	ds_read_b128 v[162:165], v255 offset:3072
	ds_read_b128 v[166:169], v255 offset:16384
	ds_read_b128 v[170:173], v255 offset:17408
	ds_read_b128 v[190:193], v255 offset:18432
	ds_read_b128 v[194:197], v255 offset:19456
	s_add_i32 m0, s9, 0xc000
	ds_read_b128 v[198:201], v148
	ds_read_b128 v[202:205], v148 offset:1024
	ds_read_b128 v[206:209], v148 offset:2048
	ds_read_b128 v[218:221], v148 offset:3072
	ds_read_b128 v[222:225], v148 offset:4096
	ds_read_b128 v[226:229], v148 offset:5120
	ds_read_b128 v[230:233], v148 offset:6144
	ds_read_b128 v[234:237], v148 offset:7168
	global_load_lds_dwordx4 v130, s[18:19]
	s_add_i32 m0, s9, 0xe000
	s_nop 0
	global_load_lds_dwordx4 v134, s[18:19]
	s_waitcnt vmcnt(8)
	s_waitcnt lgkmcnt(0)
	s_barrier
	s_setprio 1
	s_waitcnt lgkmcnt(0)
	v_mfma_f32_16x16x32_bf16 v[126:129], v[150:153], v[198:201], 0
	v_mfma_f32_16x16x32_bf16 v[122:125], v[158:161], v[198:201], 0
	v_mfma_f32_16x16x32_bf16 v[110:113], v[150:153], v[206:209], 0
	v_mfma_f32_16x16x32_bf16 v[106:109], v[158:161], v[206:209], 0
	v_mfma_f32_16x16x32_bf16 v[94:97], v[150:153], v[222:225], 0
	v_mfma_f32_16x16x32_bf16 v[90:93], v[158:161], v[222:225], 0
	v_mfma_f32_16x16x32_bf16 v[82:85], v[150:153], v[230:233], 0
	v_mfma_f32_16x16x32_bf16 v[74:77], v[158:161], v[230:233], 0
	v_mfma_f32_16x16x32_bf16 v[126:129], v[154:157], v[202:205], v[126:129]
	v_mfma_f32_16x16x32_bf16 v[122:125], v[162:165], v[202:205], v[122:125]
	v_mfma_f32_16x16x32_bf16 v[110:113], v[154:157], v[218:221], v[110:113]
	v_mfma_f32_16x16x32_bf16 v[106:109], v[162:165], v[218:221], v[106:109]
	v_mfma_f32_16x16x32_bf16 v[94:97], v[154:157], v[226:229], v[94:97]
	v_mfma_f32_16x16x32_bf16 v[90:93], v[162:165], v[226:229], v[90:93]
	v_mfma_f32_16x16x32_bf16 v[82:85], v[154:157], v[234:237], v[82:85]
	v_mfma_f32_16x16x32_bf16 v[74:77], v[162:165], v[234:237], v[74:77]
	s_setprio 0
	s_setprio 1
	v_mfma_f32_16x16x32_bf16 v[118:121], v[166:169], v[198:201], 0
	v_mfma_f32_16x16x32_bf16 v[114:117], v[190:193], v[198:201], 0
	v_mfma_f32_16x16x32_bf16 v[102:105], v[166:169], v[206:209], 0
	v_mfma_f32_16x16x32_bf16 v[98:101], v[190:193], v[206:209], 0
	v_mfma_f32_16x16x32_bf16 v[86:89], v[166:169], v[222:225], 0
	v_mfma_f32_16x16x32_bf16 v[78:81], v[190:193], v[222:225], 0
	v_mfma_f32_16x16x32_bf16 v[70:73], v[166:169], v[230:233], 0
	v_mfma_f32_16x16x32_bf16 v[66:69], v[190:193], v[230:233], 0
	v_mfma_f32_16x16x32_bf16 v[118:121], v[170:173], v[202:205], v[118:121]
	v_mfma_f32_16x16x32_bf16 v[114:117], v[194:197], v[202:205], v[114:117]
	v_mfma_f32_16x16x32_bf16 v[102:105], v[170:173], v[218:221], v[102:105]
	v_mfma_f32_16x16x32_bf16 v[98:101], v[194:197], v[218:221], v[98:101]
	v_mfma_f32_16x16x32_bf16 v[86:89], v[170:173], v[226:229], v[86:89]
	v_mfma_f32_16x16x32_bf16 v[78:81], v[194:197], v[226:229], v[78:81]
	v_mfma_f32_16x16x32_bf16 v[70:73], v[170:173], v[234:237], v[70:73]
	v_mfma_f32_16x16x32_bf16 v[66:69], v[194:197], v[234:237], v[66:69]
	s_setprio 0
	s_barrier
	s_add_i32 s79, s79, s8
	s_mov_b32 m0, s79
	ds_read_b128 v[198:201], v148 offset:16384
	ds_read_b128 v[202:205], v148 offset:17408
	ds_read_b128 v[206:209], v148 offset:18432
	ds_read_b128 v[218:221], v148 offset:19456
	ds_read_b128 v[222:225], v148 offset:20480
	ds_read_b128 v[226:229], v148 offset:21504
	ds_read_b128 v[230:233], v148 offset:22528
	ds_read_b128 v[234:237], v148 offset:23552
	global_load_lds_dwordx4 v132, s[76:77]
	s_add_i32 m0, s79, 0x2000
	s_add_u32 s80, s76, 0x40000
	s_addc_u32 s81, s77, 0
	s_add_i32 s79, s82, s8
	global_load_lds_dwordx4 v136, s[76:77]
	s_mov_b32 m0, s79
	s_nop 0
	global_load_lds_dwordx4 v132, s[80:81]
	s_add_i32 m0, s79, 0x2000
	s_nop 0
	global_load_lds_dwordx4 v136, s[80:81]
	s_mov_b32 m0, s9
	s_nop 0
	global_load_lds_dwordx4 v130, s[20:21]
	s_mov_b32 m0, s28
	s_nop 0
	global_load_lds_dwordx4 v134, s[20:21]
	s_waitcnt vmcnt(8)
	s_waitcnt lgkmcnt(0)
	s_barrier
; #define PG8_STAGE(bufoff, gbase, voff) do { _Pragma("unroll") for (int _i = 0; _i < 2; ++_i) \
;         __builtin_amdgcn_global_load_lds((const unsigned*)((const char*)(gbase) + (voff)[_i]), (LAS unsigned*)(lds + (bufoff) + ldsw + _i * 8192), 16, 0, 0); } while (0)
; #define PG8_LDA(dst, b, h) do { _Pragma("unroll") for (int m = 0; m < 4; ++m) _Pragma("unroll") for (int k = 0; k < 2; ++k) dst[m][k] = *(const LAS bf16x8*)(lds + PG8_SA(b, h) + aoff + m * 2048 + k * 1024); } while (0)
; #define PG8_LDB(dst, b, h) do { _Pragma("unroll") for (int n = 0; n < 2; ++n) _Pragma("unroll") for (int k = 0; k < 2; ++k) dst[n][k] = *(const LAS bf16x8*)(lds + PG8_SB(b, h) + boff + n * 2048 + k * 1024); } while (0)
; #define PG8_MMA(ai, bj, At, Bt) do { __builtin_amdgcn_s_setprio(1); _Pragma("unroll") for (int m = 0; m < 4; ++m) _Pragma("unroll") for (int n = 0; n < 2; ++n) _Pragma("unroll") for (int k = 0; k < 2; ++k) \
;         acc[ai][bj][m][n] = __builtin_amdgcn_mfma_f32_16x16x32_bf16(Bt[n][k], At[m][k], acc[ai][bj][m][n], 0, 0, 0); __builtin_amdgcn_s_setprio(0); } while (0)
; #define PG8_WAIT_V(n) asm volatile("s_waitcnt vmcnt(" #n ")" ::: "memory")
; #define PG8_WAIT_L(n) asm volatile("s_waitcnt lgkmcnt(" #n ")" ::: "memory")
; #define PG8_BAR __builtin_amdgcn_s_barrier()
; #define PG8_SCHED __builtin_amdgcn_sched_barrier(0)
; template <class Epi, class Sched>
; __device__ __forceinline__ void gemm_phase(LAS unsigned char* lds, const Gemm g, const Sched& S, const Epi& E) {
;     ...
;             PG8_WAIT_V(8); PG8_WAIT_L(0); PG8_BAR; PG8_MMA(1, 0, At, B0); PG8_MMA(1, 1, At, B1); PG8_BAR; PG8_SCHED;
;             PG8_LDB(B0, 1, 0); PG8_LDB(B1, 1, 1); PG8_SCHED; PG8_LDA(At, 1, 0); PG8_STAGE(PG8_SA(0, 1), a2 + hstepA, voffA);
;             PG8_WAIT_V(8); PG8_WAIT_L(0); PG8_BAR; PG8_MMA(0, 0, At, B0); PG8_MMA(0, 1, At, B1); PG8_BAR; PG8_SCHED;
	s_setprio 1
	s_waitcnt lgkmcnt(0)
	v_mfma_f32_16x16x32_bf16 v[62:65], v[150:153], v[198:201], 0
	v_mfma_f32_16x16x32_bf16 v[58:61], v[158:161], v[198:201], 0
	v_mfma_f32_16x16x32_bf16 v[50:53], v[150:153], v[206:209], 0
	v_mfma_f32_16x16x32_bf16 v[42:45], v[158:161], v[206:209], 0
	v_mfma_f32_16x16x32_bf16 v[30:33], v[150:153], v[222:225], 0
	v_mfma_f32_16x16x32_bf16 v[26:29], v[158:161], v[222:225], 0
	v_mfma_f32_16x16x32_bf16 v[18:21], v[150:153], v[230:233], 0
	v_mfma_f32_16x16x32_bf16 v[10:13], v[158:161], v[230:233], 0
	v_mfma_f32_16x16x32_bf16 v[62:65], v[154:157], v[202:205], v[62:65]
	v_mfma_f32_16x16x32_bf16 v[58:61], v[162:165], v[202:205], v[58:61]
	v_mfma_f32_16x16x32_bf16 v[50:53], v[154:157], v[218:221], v[50:53]
	v_mfma_f32_16x16x32_bf16 v[42:45], v[162:165], v[218:221], v[42:45]
	v_mfma_f32_16x16x32_bf16 v[30:33], v[154:157], v[226:229], v[30:33]
	v_mfma_f32_16x16x32_bf16 v[26:29], v[162:165], v[226:229], v[26:29]
	v_mfma_f32_16x16x32_bf16 v[18:21], v[154:157], v[234:237], v[18:21]
	v_mfma_f32_16x16x32_bf16 v[10:13], v[162:165], v[234:237], v[10:13]
	s_setprio 0
	s_setprio 1
	v_mfma_f32_16x16x32_bf16 v[54:57], v[166:169], v[198:201], 0
	v_mfma_f32_16x16x32_bf16 v[46:49], v[190:193], v[198:201], 0
	v_mfma_f32_16x16x32_bf16 v[38:41], v[166:169], v[206:209], 0
	v_mfma_f32_16x16x32_bf16 v[34:37], v[190:193], v[206:209], 0
	v_mfma_f32_16x16x32_bf16 v[22:25], v[166:169], v[222:225], 0
	v_mfma_f32_16x16x32_bf16 v[14:17], v[190:193], v[222:225], 0
	v_mfma_f32_16x16x32_bf16 v[6:9], v[166:169], v[230:233], 0
	v_mfma_f32_16x16x32_bf16 v[2:5], v[190:193], v[230:233], 0
	v_mfma_f32_16x16x32_bf16 v[54:57], v[170:173], v[202:205], v[54:57]
	v_mfma_f32_16x16x32_bf16 v[46:49], v[194:197], v[202:205], v[46:49]
	v_mfma_f32_16x16x32_bf16 v[38:41], v[170:173], v[218:221], v[38:41]
	v_mfma_f32_16x16x32_bf16 v[34:37], v[194:197], v[218:221], v[34:37]
	v_mfma_f32_16x16x32_bf16 v[22:25], v[170:173], v[226:229], v[22:25]
	v_mfma_f32_16x16x32_bf16 v[14:17], v[194:197], v[226:229], v[14:17]
	v_mfma_f32_16x16x32_bf16 v[6:9], v[170:173], v[234:237], v[6:9]
	v_mfma_f32_16x16x32_bf16 v[2:5], v[194:197], v[234:237], v[2:5]
	s_setprio 0
	s_barrier
	s_add_i32 s79, 0, 0x18000
	s_add_i32 s80, 0, 0x1c000
	ds_read_b128 v[150:153], v255 offset:32768
	ds_read_b128 v[154:157], v255 offset:33792
	ds_read_b128 v[158:161], v255 offset:34816
	ds_read_b128 v[162:165], v255 offset:35840
	ds_read_b128 v[166:169], v255 offset:49152
	ds_read_b128 v[170:173], v255 offset:50176
	ds_read_b128 v[190:193], v255 offset:51200
	ds_read_b128 v[194:197], v255 offset:52224
	s_add_u32 s20, s20, 0x40000
	s_addc_u32 s21, s21, 0
	s_mov_b32 m0, s29
	ds_read_b128 v[198:201], v148 offset:32768
	ds_read_b128 v[202:205], v148 offset:33792
	ds_read_b128 v[206:209], v148 offset:34816
	ds_read_b128 v[218:221], v148 offset:35840
	ds_read_b128 v[222:225], v148 offset:36864
	ds_read_b128 v[226:229], v148 offset:37888
	ds_read_b128 v[230:233], v148 offset:38912
	ds_read_b128 v[234:237], v148 offset:39936
	global_load_lds_dwordx4 v130, s[20:21]
	s_mov_b32 m0, s30
	s_nop 0
	global_load_lds_dwordx4 v134, s[20:21]
	s_waitcnt vmcnt(8)
	s_waitcnt lgkmcnt(0)
	s_barrier
	s_setprio 1
	s_waitcnt lgkmcnt(0)
	v_mfma_f32_16x16x32_bf16 v[126:129], v[150:153], v[198:201], v[126:129]
	v_mfma_f32_16x16x32_bf16 v[122:125], v[158:161], v[198:201], v[122:125]
	v_mfma_f32_16x16x32_bf16 v[110:113], v[150:153], v[206:209], v[110:113]
	v_mfma_f32_16x16x32_bf16 v[106:109], v[158:161], v[206:209], v[106:109]
	v_mfma_f32_16x16x32_bf16 v[94:97], v[150:153], v[222:225], v[94:97]
	v_mfma_f32_16x16x32_bf16 v[90:93], v[158:161], v[222:225], v[90:93]
	v_mfma_f32_16x16x32_bf16 v[82:85], v[150:153], v[230:233], v[82:85]
	v_mfma_f32_16x16x32_bf16 v[74:77], v[158:161], v[230:233], v[74:77]
	v_mfma_f32_16x16x32_bf16 v[126:129], v[154:157], v[202:205], v[126:129]
	v_mfma_f32_16x16x32_bf16 v[122:125], v[162:165], v[202:205], v[122:125]
	v_mfma_f32_16x16x32_bf16 v[110:113], v[154:157], v[218:221], v[110:113]
	v_mfma_f32_16x16x32_bf16 v[106:109], v[162:165], v[218:221], v[106:109]
	v_mfma_f32_16x16x32_bf16 v[94:97], v[154:157], v[226:229], v[94:97]
	v_mfma_f32_16x16x32_bf16 v[90:93], v[162:165], v[226:229], v[90:93]
	v_mfma_f32_16x16x32_bf16 v[82:85], v[154:157], v[234:237], v[82:85]
	v_mfma_f32_16x16x32_bf16 v[74:77], v[162:165], v[234:237], v[74:77]
	s_setprio 0
	s_setprio 1
	v_mfma_f32_16x16x32_bf16 v[118:121], v[166:169], v[198:201], v[118:121]
	v_mfma_f32_16x16x32_bf16 v[114:117], v[190:193], v[198:201], v[114:117]
	v_mfma_f32_16x16x32_bf16 v[102:105], v[166:169], v[206:209], v[102:105]
	v_mfma_f32_16x16x32_bf16 v[98:101], v[190:193], v[206:209], v[98:101]
	v_mfma_f32_16x16x32_bf16 v[86:89], v[166:169], v[222:225], v[86:89]
	v_mfma_f32_16x16x32_bf16 v[78:81], v[190:193], v[222:225], v[78:81]
	v_mfma_f32_16x16x32_bf16 v[70:73], v[166:169], v[230:233], v[70:73]
	v_mfma_f32_16x16x32_bf16 v[66:69], v[190:193], v[230:233], v[66:69]
	v_mfma_f32_16x16x32_bf16 v[118:121], v[170:173], v[202:205], v[118:121]
	v_mfma_f32_16x16x32_bf16 v[114:117], v[194:197], v[202:205], v[114:117]
	v_mfma_f32_16x16x32_bf16 v[102:105], v[170:173], v[218:221], v[102:105]
	v_mfma_f32_16x16x32_bf16 v[98:101], v[194:197], v[218:221], v[98:101]
	v_mfma_f32_16x16x32_bf16 v[86:89], v[170:173], v[226:229], v[86:89]
	v_mfma_f32_16x16x32_bf16 v[78:81], v[194:197], v[226:229], v[78:81]
	v_mfma_f32_16x16x32_bf16 v[70:73], v[170:173], v[234:237], v[70:73]
	v_mfma_f32_16x16x32_bf16 v[66:69], v[194:197], v[234:237], v[66:69]
	s_setprio 0
	s_barrier
; #define PG8_STAGE(bufoff, gbase, voff) do { _Pragma("unroll") for (int _i = 0; _i < 2; ++_i) \
;         __builtin_amdgcn_global_load_lds((const unsigned*)((const char*)(gbase) + (voff)[_i]), (LAS unsigned*)(lds + (bufoff) + ldsw + _i * 8192), 16, 0, 0); } while (0)
; #define PG8_LDA(dst, b, h) do { _Pragma("unroll") for (int m = 0; m < 4; ++m) _Pragma("unroll") for (int k = 0; k < 2; ++k) dst[m][k] = *(const LAS bf16x8*)(lds + PG8_SA(b, h) + aoff + m * 2048 + k * 1024); } while (0)
; #define PG8_MMA(ai, bj, At, Bt) do { __builtin_amdgcn_s_setprio(1); _Pragma("unroll") for (int m = 0; m < 4; ++m) _Pragma("unroll") for (int n = 0; n < 2; ++n) _Pragma("unroll") for (int k = 0; k < 2; ++k) \
;         acc[ai][bj][m][n] = __builtin_amdgcn_mfma_f32_16x16x32_bf16(Bt[n][k], At[m][k], acc[ai][bj][m][n], 0, 0, 0); __builtin_amdgcn_s_setprio(0); } while (0)
; #define PG8_WAIT_V(n) asm volatile("s_waitcnt vmcnt(" #n ")" ::: "memory")
; #define PG8_WAIT_L(n) asm volatile("s_waitcnt lgkmcnt(" #n ")" ::: "memory")
; #define PG8_BAR __builtin_amdgcn_s_barrier()
; #define PG8_SCHED __builtin_amdgcn_sched_barrier(0)
; template <class Epi, class Sched>
; __device__ __forceinline__ void gemm_phase(LAS unsigned char* lds, const Gemm g, const Sched& S, const Epi& E) {
;     ...
;             PG8_LDA(At, 1, 1); PG8_STAGE(PG8_SB(1, 0), b3, voffB); PG8_STAGE(PG8_SB(1, 1), b3 + hstepB, voffB); PG8_STAGE(PG8_SA(1, 0), a3, voffA);
;             PG8_WAIT_V(8); PG8_WAIT_L(0); PG8_BAR; PG8_MMA(1, 0, At, B0); PG8_MMA(1, 1, At, B1); PG8_BAR; PG8_SCHED;
;         }
	s_add_i32 s20, s8, 0x18000
	s_add_u32 s80, s76, 0x80
	s_addc_u32 s81, s77, 0
	s_mov_b32 m0, s20
	ds_read_b128 v[198:201], v148 offset:49152
	ds_read_b128 v[202:205], v148 offset:50176
	ds_read_b128 v[206:209], v148 offset:51200
	ds_read_b128 v[218:221], v148 offset:52224
	ds_read_b128 v[222:225], v148 offset:53248
	ds_read_b128 v[226:229], v148 offset:54272
	ds_read_b128 v[230:233], v148 offset:55296
	ds_read_b128 v[234:237], v148 offset:56320
	global_load_lds_dwordx4 v132, s[80:81]
	s_add_i32 m0, s20, 0x2000
	s_add_u32 s20, s76, 0x40080
	s_addc_u32 s21, s77, 0
	s_add_i32 s12, s8, 0x1c000
	global_load_lds_dwordx4 v136, s[80:81]
	s_mov_b32 m0, s12
	s_nop 0
	global_load_lds_dwordx4 v132, s[20:21]
	s_add_i32 m0, s12, 0x2000
	s_nop 0
	global_load_lds_dwordx4 v136, s[20:21]
	s_mov_b32 m0, s31
	s_nop 0
	global_load_lds_dwordx4 v130, s[100:101]
	s_mov_b32 m0, s34
	s_nop 0
	global_load_lds_dwordx4 v134, s[100:101]
	s_waitcnt vmcnt(8)
	s_waitcnt lgkmcnt(0)
	s_barrier
	s_setprio 1
	s_waitcnt lgkmcnt(0)
	v_mfma_f32_16x16x32_bf16 v[62:65], v[150:153], v[198:201], v[62:65]
	v_mfma_f32_16x16x32_bf16 v[58:61], v[158:161], v[198:201], v[58:61]
	v_mfma_f32_16x16x32_bf16 v[50:53], v[150:153], v[206:209], v[50:53]
	v_mfma_f32_16x16x32_bf16 v[42:45], v[158:161], v[206:209], v[42:45]
	v_mfma_f32_16x16x32_bf16 v[30:33], v[150:153], v[222:225], v[30:33]
	v_mfma_f32_16x16x32_bf16 v[26:29], v[158:161], v[222:225], v[26:29]
	v_mfma_f32_16x16x32_bf16 v[18:21], v[150:153], v[230:233], v[18:21]
	v_mfma_f32_16x16x32_bf16 v[10:13], v[158:161], v[230:233], v[10:13]
	v_mfma_f32_16x16x32_bf16 v[62:65], v[154:157], v[202:205], v[62:65]
	v_mfma_f32_16x16x32_bf16 v[58:61], v[162:165], v[202:205], v[58:61]
	v_mfma_f32_16x16x32_bf16 v[50:53], v[154:157], v[218:221], v[50:53]
	v_mfma_f32_16x16x32_bf16 v[42:45], v[162:165], v[218:221], v[42:45]
	v_mfma_f32_16x16x32_bf16 v[30:33], v[154:157], v[226:229], v[30:33]
	v_mfma_f32_16x16x32_bf16 v[26:29], v[162:165], v[226:229], v[26:29]
	v_mfma_f32_16x16x32_bf16 v[18:21], v[154:157], v[234:237], v[18:21]
	v_mfma_f32_16x16x32_bf16 v[10:13], v[162:165], v[234:237], v[10:13]
	s_setprio 0
	s_setprio 1
	v_mfma_f32_16x16x32_bf16 v[54:57], v[166:169], v[198:201], v[54:57]
	v_mfma_f32_16x16x32_bf16 v[46:49], v[190:193], v[198:201], v[46:49]
	v_mfma_f32_16x16x32_bf16 v[38:41], v[166:169], v[206:209], v[38:41]
	v_mfma_f32_16x16x32_bf16 v[34:37], v[190:193], v[206:209], v[34:37]
	v_mfma_f32_16x16x32_bf16 v[22:25], v[166:169], v[222:225], v[22:25]
	v_mfma_f32_16x16x32_bf16 v[14:17], v[190:193], v[222:225], v[14:17]
	v_mfma_f32_16x16x32_bf16 v[6:9], v[166:169], v[230:233], v[6:9]
	v_mfma_f32_16x16x32_bf16 v[2:5], v[190:193], v[230:233], v[2:5]
	v_mfma_f32_16x16x32_bf16 v[54:57], v[170:173], v[202:205], v[54:57]
	v_mfma_f32_16x16x32_bf16 v[46:49], v[194:197], v[202:205], v[46:49]
	v_mfma_f32_16x16x32_bf16 v[38:41], v[170:173], v[218:221], v[38:41]
	v_mfma_f32_16x16x32_bf16 v[34:37], v[194:197], v[218:221], v[34:37]
	v_mfma_f32_16x16x32_bf16 v[22:25], v[170:173], v[226:229], v[22:25]
	v_mfma_f32_16x16x32_bf16 v[14:17], v[194:197], v[226:229], v[14:17]
	v_mfma_f32_16x16x32_bf16 v[6:9], v[170:173], v[234:237], v[6:9]
	v_mfma_f32_16x16x32_bf16 v[2:5], v[194:197], v[234:237], v[2:5]
	s_setprio 0
	s_barrier
	s_add_i32 s78, s78, 2
	s_add_u32 s18, s18, 0x100
	s_addc_u32 s19, s19, 0
	s_add_u32 s69, s69, 0x100
	s_addc_u32 s71, s71, 0
	s_cmp_gt_u32 s78, 13

; #define PG8_STAGE(bufoff, gbase, voff) do { _Pragma("unroll") for (int _i = 0; _i < 2; ++_i) \
;         __builtin_amdgcn_global_load_lds((const unsigned*)((const char*)(gbase) + (voff)[_i]), (LAS unsigned*)(lds + (bufoff) + ldsw + _i * 8192), 16, 0, 0); } while (0)
; #define PG8_LDA(dst, b, h) do { _Pragma("unroll") for (int m = 0; m < 4; ++m) _Pragma("unroll") for (int k = 0; k < 2; ++k) dst[m][k] = *(const LAS bf16x8*)(lds + PG8_SA(b, h) + aoff + m * 2048 + k * 1024); } while (0)
; #define PG8_LDB(dst, b, h) do { _Pragma("unroll") for (int n = 0; n < 2; ++n) _Pragma("unroll") for (int k = 0; k < 2; ++k) dst[n][k] = *(const LAS bf16x8*)(lds + PG8_SB(b, h) + boff + n * 2048 + k * 1024); } while (0)
; #define PG8_MMA(ai, bj, At, Bt) do { __builtin_amdgcn_s_setprio(1); _Pragma("unroll") for (int m = 0; m < 4; ++m) _Pragma("unroll") for (int n = 0; n < 2; ++n) _Pragma("unroll") for (int k = 0; k < 2; ++k) \
;         acc[ai][bj][m][n] = __builtin_amdgcn_mfma_f32_16x16x32_bf16(Bt[n][k], At[m][k], acc[ai][bj][m][n], 0, 0, 0); __builtin_amdgcn_s_setprio(0); } while (0)
; #define PG8_WAIT_V(n) asm volatile("s_waitcnt vmcnt(" #n ")" ::: "memory")
; #define PG8_WAIT_L(n) asm volatile("s_waitcnt lgkmcnt(" #n ")" ::: "memory")
; template <class Epi, class Sched>
; __device__ __forceinline__ void gemm_phase(LAS unsigned char* lds, const Gemm g, const Sched& S, const Epi& E) {
;     ...
;         const bool has_next = S.next(ui + 1, nxt);
;         const char* nA = has_next ? (const char*)g.A + (size_t)nxt.pm * tstepA + (size_t)nxt.pn * g.a_pn_off * 2 : cA; const char* nB = has_next ? (const char*)g.Bt + (size_t)nxt.pn * tstepB : cB;
;         for (int t = 0; t < nt; t += 2) {
;             const bool last = (t == nt - 2);
;             const char* a1 = cA + (size_t)(t + 1) * kstep;
;             const char* a2 = last ? nA : cA + (size_t)(t + 2) * kstep; const char* b2 = last ? nB : cB + (size_t)(t + 2) * kstep;
;             const char* a3 = a2 + kstep; const char* b3 = b2 + kstep;
;             PG8_LDB(B0, 0, 0); PG8_LDB(B1, 0, 1); PG8_SCHED; PG8_LDA(At, 0, 0); PG8_STAGE(PG8_SA(1, 1), a1 + hstepA, voffA);
;             PG8_WAIT_V(8); PG8_WAIT_L(0); PG8_BAR; PG8_MMA(0, 0, At, B0); PG8_MMA(0, 1, At, B1); PG8_BAR; PG8_SCHED;
;             PG8_LDA(At, 0, 1); PG8_STAGE(PG8_SB(0, 0), b2, voffB); PG8_STAGE(PG8_SB(0, 1), b2 + hstepB, voffB); PG8_STAGE(PG8_SA(0, 0), a2, voffA);
.LBB0_377:
	s_ashr_i32 s71, s70, 31
	s_lshl_b64 s[48:49], s[70:71], 19
	v_readlane_b32 s12, v248, 21
	s_add_u32 s72, s12, s48
	v_readlane_b32 s12, v248, 22
	s_addc_u32 s73, s12, s49
	s_and_b64 s[48:49], s[66:67], exec
	s_cselect_b32 s43, s73, s19
	s_cselect_b32 s48, s72, s18
	s_ashr_i32 s69, s68, 31
	s_lshl_b64 s[74:75], s[68:69], 19
	s_add_u32 s74, s4, s74
	s_addc_u32 s75, s5, s75
	s_and_b64 s[76:77], s[66:67], exec
	s_cselect_b32 s49, s75, s21
	s_cselect_b32 s53, s74, s20
	s_add_u32 s18, s18, 0x40080
	s_addc_u32 s19, s19, 0
	s_add_u32 s69, s20, 0x100
	s_addc_u32 s71, s21, 0
	s_mov_b32 s78, -2
	v_add_u32_e32 v255, 0x10000, v158
	s_add_u32 s20, s18, 0xfffc0080
	s_addc_u32 s21, s19, -1
	s_add_i32 s79, 0, 0x10000
	s_cmp_eq_u32 s78, 12
	s_cselect_b32 s21, s43, s21
	s_cselect_b32 s20, s48, s20
	s_cselect_b32 s77, s49, s71
	s_cselect_b32 s76, s53, s69
	s_add_u32 s100, s20, 0x80
	s_addc_u32 s101, s21, 0
	s_add_i32 s82, 0, 0x14000
	ds_read_b128 v[130:133], v255
	ds_read_b128 v[134:137], v255 offset:1024
	ds_read_b128 v[138:141], v255 offset:2048
	ds_read_b128 v[142:145], v255 offset:3072
	ds_read_b128 v[162:165], v255 offset:16384
	ds_read_b128 v[166:169], v255 offset:17408
	ds_read_b128 v[170:173], v255 offset:18432
	ds_read_b128 v[190:193], v255 offset:19456
	s_add_i32 m0, s9, 0xc000
	ds_read_b128 v[194:197], v160
	ds_read_b128 v[198:201], v160 offset:1024
	ds_read_b128 v[202:205], v160 offset:2048
	ds_read_b128 v[206:209], v160 offset:3072
	ds_read_b128 v[218:221], v160 offset:4096
	ds_read_b128 v[222:225], v160 offset:5120
	ds_read_b128 v[226:229], v160 offset:6144
	ds_read_b128 v[230:233], v160 offset:7168
	global_load_lds_dwordx4 v146, s[18:19]
	s_add_i32 m0, s9, 0xe000
	s_nop 0
	global_load_lds_dwordx4 v150, s[18:19]
	s_waitcnt vmcnt(8)
	s_waitcnt lgkmcnt(0)
	s_barrier
	s_setprio 1
	s_waitcnt lgkmcnt(0)
	v_mfma_f32_16x16x32_bf16 v[126:129], v[130:133], v[194:197], 0
	v_mfma_f32_16x16x32_bf16 v[122:125], v[138:141], v[194:197], 0
	v_mfma_f32_16x16x32_bf16 v[118:121], v[130:133], v[202:205], 0
	v_mfma_f32_16x16x32_bf16 v[110:113], v[138:141], v[202:205], 0
	v_mfma_f32_16x16x32_bf16 v[102:105], v[130:133], v[218:221], 0
	v_mfma_f32_16x16x32_bf16 v[94:97], v[138:141], v[218:221], 0
	v_mfma_f32_16x16x32_bf16 v[86:89], v[130:133], v[226:229], 0
	v_mfma_f32_16x16x32_bf16 v[78:81], v[138:141], v[226:229], 0
	v_mfma_f32_16x16x32_bf16 v[126:129], v[134:137], v[198:201], v[126:129]
	v_mfma_f32_16x16x32_bf16 v[122:125], v[142:145], v[198:201], v[122:125]
	v_mfma_f32_16x16x32_bf16 v[118:121], v[134:137], v[206:209], v[118:121]
	v_mfma_f32_16x16x32_bf16 v[110:113], v[142:145], v[206:209], v[110:113]
	v_mfma_f32_16x16x32_bf16 v[102:105], v[134:137], v[222:225], v[102:105]
	v_mfma_f32_16x16x32_bf16 v[94:97], v[142:145], v[222:225], v[94:97]
	v_mfma_f32_16x16x32_bf16 v[86:89], v[134:137], v[230:233], v[86:89]
	v_mfma_f32_16x16x32_bf16 v[78:81], v[142:145], v[230:233], v[78:81]
	s_setprio 0
	s_setprio 1
	v_mfma_f32_16x16x32_bf16 v[114:117], v[162:165], v[194:197], 0
	v_mfma_f32_16x16x32_bf16 v[106:109], v[170:173], v[194:197], 0
	v_mfma_f32_16x16x32_bf16 v[98:101], v[162:165], v[202:205], 0
	v_mfma_f32_16x16x32_bf16 v[90:93], v[170:173], v[202:205], 0
	v_mfma_f32_16x16x32_bf16 v[82:85], v[162:165], v[218:221], 0
	v_mfma_f32_16x16x32_bf16 v[74:77], v[170:173], v[218:221], 0
	v_mfma_f32_16x16x32_bf16 v[70:73], v[162:165], v[226:229], 0
	v_mfma_f32_16x16x32_bf16 v[66:69], v[170:173], v[226:229], 0
	v_mfma_f32_16x16x32_bf16 v[114:117], v[166:169], v[198:201], v[114:117]
	v_mfma_f32_16x16x32_bf16 v[106:109], v[190:193], v[198:201], v[106:109]
	v_mfma_f32_16x16x32_bf16 v[98:101], v[166:169], v[206:209], v[98:101]
	v_mfma_f32_16x16x32_bf16 v[90:93], v[190:193], v[206:209], v[90:93]
	v_mfma_f32_16x16x32_bf16 v[82:85], v[166:169], v[222:225], v[82:85]
	v_mfma_f32_16x16x32_bf16 v[74:77], v[190:193], v[222:225], v[74:77]
	v_mfma_f32_16x16x32_bf16 v[70:73], v[166:169], v[230:233], v[70:73]
	v_mfma_f32_16x16x32_bf16 v[66:69], v[190:193], v[230:233], v[66:69]
	s_setprio 0
	s_barrier
	s_add_i32 s79, s79, s8
	s_mov_b32 m0, s79
	ds_read_b128 v[194:197], v160 offset:16384
	ds_read_b128 v[198:201], v160 offset:17408
	ds_read_b128 v[202:205], v160 offset:18432
	ds_read_b128 v[206:209], v160 offset:19456
	ds_read_b128 v[218:221], v160 offset:20480
	ds_read_b128 v[222:225], v160 offset:21504
	ds_read_b128 v[226:229], v160 offset:22528
	ds_read_b128 v[230:233], v160 offset:23552
	global_load_lds_dwordx4 v148, s[76:77]
	s_add_i32 m0, s79, 0x2000
	s_add_u32 s80, s76, 0x40000
	s_addc_u32 s81, s77, 0
	s_add_i32 s79, s82, s8
	global_load_lds_dwordx4 v152, s[76:77]
	s_mov_b32 m0, s79
	s_nop 0
	global_load_lds_dwordx4 v148, s[80:81]
	s_add_i32 m0, s79, 0x2000
	s_nop 0
	global_load_lds_dwordx4 v152, s[80:81]
	s_mov_b32 m0, s9
	s_nop 0
	global_load_lds_dwordx4 v146, s[20:21]
	s_mov_b32 m0, s28
	s_nop 0
	global_load_lds_dwordx4 v150, s[20:21]
	s_waitcnt vmcnt(8)
	s_waitcnt lgkmcnt(0)
	s_barrier
; #define PG8_STAGE(bufoff, gbase, voff) do { _Pragma("unroll") for (int _i = 0; _i < 2; ++_i) \
;         __builtin_amdgcn_global_load_lds((const unsigned*)((const char*)(gbase) + (voff)[_i]), (LAS unsigned*)(lds + (bufoff) + ldsw + _i * 8192), 16, 0, 0); } while (0)
; #define PG8_LDA(dst, b, h) do { _Pragma("unroll") for (int m = 0; m < 4; ++m) _Pragma("unroll") for (int k = 0; k < 2; ++k) dst[m][k] = *(const LAS bf16x8*)(lds + PG8_SA(b, h) + aoff + m * 2048 + k * 1024); } while (0)
; #define PG8_LDB(dst, b, h) do { _Pragma("unroll") for (int n = 0; n < 2; ++n) _Pragma("unroll") for (int k = 0; k < 2; ++k) dst[n][k] = *(const LAS bf16x8*)(lds + PG8_SB(b, h) + boff + n * 2048 + k * 1024); } while (0)
; #define PG8_MMA(ai, bj, At, Bt) do { __builtin_amdgcn_s_setprio(1); _Pragma("unroll") for (int m = 0; m < 4; ++m) _Pragma("unroll") for (int n = 0; n < 2; ++n) _Pragma("unroll") for (int k = 0; k < 2; ++k) \
;         acc[ai][bj][m][n] = __builtin_amdgcn_mfma_f32_16x16x32_bf16(Bt[n][k], At[m][k], acc[ai][bj][m][n], 0, 0, 0); __builtin_amdgcn_s_setprio(0); } while (0)
; #define PG8_WAIT_V(n) asm volatile("s_waitcnt vmcnt(" #n ")" ::: "memory")
; #define PG8_WAIT_L(n) asm volatile("s_waitcnt lgkmcnt(" #n ")" ::: "memory")
; #define PG8_BAR __builtin_amdgcn_s_barrier()
; #define PG8_SCHED __builtin_amdgcn_sched_barrier(0)
; template <class Epi, class Sched>
; __device__ __forceinline__ void gemm_phase(LAS unsigned char* lds, const Gemm g, const Sched& S, const Epi& E) {
;     ...
;             PG8_WAIT_V(8); PG8_WAIT_L(0); PG8_BAR; PG8_MMA(1, 0, At, B0); PG8_MMA(1, 1, At, B1); PG8_BAR; PG8_SCHED;
;             PG8_LDB(B0, 1, 0); PG8_LDB(B1, 1, 1); PG8_SCHED; PG8_LDA(At, 1, 0); PG8_STAGE(PG8_SA(0, 1), a2 + hstepA, voffA);
;             PG8_WAIT_V(8); PG8_WAIT_L(0); PG8_BAR; PG8_MMA(0, 0, At, B0); PG8_MMA(0, 1, At, B1); PG8_BAR; PG8_SCHED;
	s_setprio 1
	s_waitcnt lgkmcnt(0)
	v_mfma_f32_16x16x32_bf16 v[62:65], v[130:133], v[194:197], 0
	v_mfma_f32_16x16x32_bf16 v[58:61], v[138:141], v[194:197], 0
	v_mfma_f32_16x16x32_bf16 v[54:57], v[130:133], v[202:205], 0
	v_mfma_f32_16x16x32_bf16 v[46:49], v[138:141], v[202:205], 0
	v_mfma_f32_16x16x32_bf16 v[38:41], v[130:133], v[218:221], 0
	v_mfma_f32_16x16x32_bf16 v[30:33], v[138:141], v[218:221], 0
	v_mfma_f32_16x16x32_bf16 v[22:25], v[130:133], v[226:229], 0
	v_mfma_f32_16x16x32_bf16 v[14:17], v[138:141], v[226:229], 0
	v_mfma_f32_16x16x32_bf16 v[62:65], v[134:137], v[198:201], v[62:65]
	v_mfma_f32_16x16x32_bf16 v[58:61], v[142:145], v[198:201], v[58:61]
	v_mfma_f32_16x16x32_bf16 v[54:57], v[134:137], v[206:209], v[54:57]
	v_mfma_f32_16x16x32_bf16 v[46:49], v[142:145], v[206:209], v[46:49]
	v_mfma_f32_16x16x32_bf16 v[38:41], v[134:137], v[222:225], v[38:41]
	v_mfma_f32_16x16x32_bf16 v[30:33], v[142:145], v[222:225], v[30:33]
	v_mfma_f32_16x16x32_bf16 v[22:25], v[134:137], v[230:233], v[22:25]
	v_mfma_f32_16x16x32_bf16 v[14:17], v[142:145], v[230:233], v[14:17]
	s_setprio 0
	s_setprio 1
	v_mfma_f32_16x16x32_bf16 v[50:53], v[162:165], v[194:197], 0
	v_mfma_f32_16x16x32_bf16 v[42:45], v[170:173], v[194:197], 0
	v_mfma_f32_16x16x32_bf16 v[34:37], v[162:165], v[202:205], 0
	v_mfma_f32_16x16x32_bf16 v[26:29], v[170:173], v[202:205], 0
	v_mfma_f32_16x16x32_bf16 v[18:21], v[162:165], v[218:221], 0
	v_mfma_f32_16x16x32_bf16 v[10:13], v[170:173], v[218:221], 0
	v_mfma_f32_16x16x32_bf16 v[6:9], v[162:165], v[226:229], 0
	v_mfma_f32_16x16x32_bf16 v[2:5], v[170:173], v[226:229], 0
	v_mfma_f32_16x16x32_bf16 v[50:53], v[166:169], v[198:201], v[50:53]
	v_mfma_f32_16x16x32_bf16 v[42:45], v[190:193], v[198:201], v[42:45]
	v_mfma_f32_16x16x32_bf16 v[34:37], v[166:169], v[206:209], v[34:37]
	v_mfma_f32_16x16x32_bf16 v[26:29], v[190:193], v[206:209], v[26:29]
	v_mfma_f32_16x16x32_bf16 v[18:21], v[166:169], v[222:225], v[18:21]
	v_mfma_f32_16x16x32_bf16 v[10:13], v[190:193], v[222:225], v[10:13]
	v_mfma_f32_16x16x32_bf16 v[6:9], v[166:169], v[230:233], v[6:9]
	v_mfma_f32_16x16x32_bf16 v[2:5], v[190:193], v[230:233], v[2:5]
	s_setprio 0
	s_barrier
	s_add_i32 s79, 0, 0x18000
	s_add_i32 s80, 0, 0x1c000
	ds_read_b128 v[130:133], v255 offset:32768
	ds_read_b128 v[134:137], v255 offset:33792
	ds_read_b128 v[138:141], v255 offset:34816
	ds_read_b128 v[142:145], v255 offset:35840
	ds_read_b128 v[162:165], v255 offset:49152
	ds_read_b128 v[166:169], v255 offset:50176
	ds_read_b128 v[170:173], v255 offset:51200
	ds_read_b128 v[190:193], v255 offset:52224
	s_add_u32 s20, s20, 0x40000
	s_addc_u32 s21, s21, 0
	s_mov_b32 m0, s29
	ds_read_b128 v[194:197], v160 offset:32768
	ds_read_b128 v[198:201], v160 offset:33792
	ds_read_b128 v[202:205], v160 offset:34816
	ds_read_b128 v[206:209], v160 offset:35840
	ds_read_b128 v[218:221], v160 offset:36864
	ds_read_b128 v[222:225], v160 offset:37888
	ds_read_b128 v[226:229], v160 offset:38912
	ds_read_b128 v[230:233], v160 offset:39936
	global_load_lds_dwordx4 v146, s[20:21]
	s_mov_b32 m0, s30
	s_nop 0
	global_load_lds_dwordx4 v150, s[20:21]
	s_waitcnt vmcnt(8)
	s_waitcnt lgkmcnt(0)
	s_barrier
	s_setprio 1
	s_waitcnt lgkmcnt(0)
	v_mfma_f32_16x16x32_bf16 v[126:129], v[130:133], v[194:197], v[126:129]
	v_mfma_f32_16x16x32_bf16 v[122:125], v[138:141], v[194:197], v[122:125]
	v_mfma_f32_16x16x32_bf16 v[118:121], v[130:133], v[202:205], v[118:121]
	v_mfma_f32_16x16x32_bf16 v[110:113], v[138:141], v[202:205], v[110:113]
	v_mfma_f32_16x16x32_bf16 v[102:105], v[130:133], v[218:221], v[102:105]
	v_mfma_f32_16x16x32_bf16 v[94:97], v[138:141], v[218:221], v[94:97]
	v_mfma_f32_16x16x32_bf16 v[86:89], v[130:133], v[226:229], v[86:89]
	v_mfma_f32_16x16x32_bf16 v[78:81], v[138:141], v[226:229], v[78:81]
	v_mfma_f32_16x16x32_bf16 v[126:129], v[134:137], v[198:201], v[126:129]
	v_mfma_f32_16x16x32_bf16 v[122:125], v[142:145], v[198:201], v[122:125]
	v_mfma_f32_16x16x32_bf16 v[118:121], v[134:137], v[206:209], v[118:121]
	v_mfma_f32_16x16x32_bf16 v[110:113], v[142:145], v[206:209], v[110:113]
	v_mfma_f32_16x16x32_bf16 v[102:105], v[134:137], v[222:225], v[102:105]
	v_mfma_f32_16x16x32_bf16 v[94:97], v[142:145], v[222:225], v[94:97]
	v_mfma_f32_16x16x32_bf16 v[86:89], v[134:137], v[230:233], v[86:89]
	v_mfma_f32_16x16x32_bf16 v[78:81], v[142:145], v[230:233], v[78:81]
	s_setprio 0
	s_setprio 1
	v_mfma_f32_16x16x32_bf16 v[114:117], v[162:165], v[194:197], v[114:117]
	v_mfma_f32_16x16x32_bf16 v[106:109], v[170:173], v[194:197], v[106:109]
	v_mfma_f32_16x16x32_bf16 v[98:101], v[162:165], v[202:205], v[98:101]
	v_mfma_f32_16x16x32_bf16 v[90:93], v[170:173], v[202:205], v[90:93]
	v_mfma_f32_16x16x32_bf16 v[82:85], v[162:165], v[218:221], v[82:85]
	v_mfma_f32_16x16x32_bf16 v[74:77], v[170:173], v[218:221], v[74:77]
	v_mfma_f32_16x16x32_bf16 v[70:73], v[162:165], v[226:229], v[70:73]
	v_mfma_f32_16x16x32_bf16 v[66:69], v[170:173], v[226:229], v[66:69]
	v_mfma_f32_16x16x32_bf16 v[114:117], v[166:169], v[198:201], v[114:117]
	v_mfma_f32_16x16x32_bf16 v[106:109], v[190:193], v[198:201], v[106:109]
	v_mfma_f32_16x16x32_bf16 v[98:101], v[166:169], v[206:209], v[98:101]
	v_mfma_f32_16x16x32_bf16 v[90:93], v[190:193], v[206:209], v[90:93]
	v_mfma_f32_16x16x32_bf16 v[82:85], v[166:169], v[222:225], v[82:85]
	v_mfma_f32_16x16x32_bf16 v[74:77], v[190:193], v[222:225], v[74:77]
	v_mfma_f32_16x16x32_bf16 v[70:73], v[166:169], v[230:233], v[70:73]
	v_mfma_f32_16x16x32_bf16 v[66:69], v[190:193], v[230:233], v[66:69]
	s_setprio 0
	s_barrier
; #define PG8_STAGE(bufoff, gbase, voff) do { _Pragma("unroll") for (int _i = 0; _i < 2; ++_i) \
;         __builtin_amdgcn_global_load_lds((const unsigned*)((const char*)(gbase) + (voff)[_i]), (LAS unsigned*)(lds + (bufoff) + ldsw + _i * 8192), 16, 0, 0); } while (0)
; #define PG8_LDA(dst, b, h) do { _Pragma("unroll") for (int m = 0; m < 4; ++m) _Pragma("unroll") for (int k = 0; k < 2; ++k) dst[m][k] = *(const LAS bf16x8*)(lds + PG8_SA(b, h) + aoff + m * 2048 + k * 1024); } while (0)
; #define PG8_MMA(ai, bj, At, Bt) do { __builtin_amdgcn_s_setprio(1); _Pragma("unroll") for (int m = 0; m < 4; ++m) _Pragma("unroll") for (int n = 0; n < 2; ++n) _Pragma("unroll") for (int k = 0; k < 2; ++k) \
;         acc[ai][bj][m][n] = __builtin_amdgcn_mfma_f32_16x16x32_bf16(Bt[n][k], At[m][k], acc[ai][bj][m][n], 0, 0, 0); __builtin_amdgcn_s_setprio(0); } while (0)
; #define PG8_WAIT_V(n) asm volatile("s_waitcnt vmcnt(" #n ")" ::: "memory")
; #define PG8_WAIT_L(n) asm volatile("s_waitcnt lgkmcnt(" #n ")" ::: "memory")
; #define PG8_BAR __builtin_amdgcn_s_barrier()
; #define PG8_SCHED __builtin_amdgcn_sched_barrier(0)
; template <class Epi, class Sched>
; __device__ __forceinline__ void gemm_phase(LAS unsigned char* lds, const Gemm g, const Sched& S, const Epi& E) {
;     ...
;             PG8_LDA(At, 1, 1); PG8_STAGE(PG8_SB(1, 0), b3, voffB); PG8_STAGE(PG8_SB(1, 1), b3 + hstepB, voffB); PG8_STAGE(PG8_SA(1, 0), a3, voffA);
;             PG8_WAIT_V(8); PG8_WAIT_L(0); PG8_BAR; PG8_MMA(1, 0, At, B0); PG8_MMA(1, 1, At, B1); PG8_BAR; PG8_SCHED;
;         }
	s_add_i32 s20, s8, 0x18000
	s_add_u32 s80, s76, 0x80
	s_addc_u32 s81, s77, 0
	s_mov_b32 m0, s20
	ds_read_b128 v[194:197], v160 offset:49152
	ds_read_b128 v[198:201], v160 offset:50176
	ds_read_b128 v[202:205], v160 offset:51200
	ds_read_b128 v[206:209], v160 offset:52224
	ds_read_b128 v[218:221], v160 offset:53248
	ds_read_b128 v[222:225], v160 offset:54272
	ds_read_b128 v[226:229], v160 offset:55296
	ds_read_b128 v[230:233], v160 offset:56320
	global_load_lds_dwordx4 v148, s[80:81]
	s_add_i32 m0, s20, 0x2000
	s_add_u32 s20, s76, 0x40080
	s_addc_u32 s21, s77, 0
	s_add_i32 s12, s8, 0x1c000
	global_load_lds_dwordx4 v152, s[80:81]
	s_mov_b32 m0, s12
	s_nop 0
	global_load_lds_dwordx4 v148, s[20:21]
	s_add_i32 m0, s12, 0x2000
	s_nop 0
	global_load_lds_dwordx4 v152, s[20:21]
	s_mov_b32 m0, s31
	s_nop 0
	global_load_lds_dwordx4 v146, s[100:101]
	s_mov_b32 m0, s34
	s_nop 0
	global_load_lds_dwordx4 v150, s[100:101]
	s_waitcnt vmcnt(8)
	s_waitcnt lgkmcnt(0)
	s_barrier
	s_setprio 1
	s_waitcnt lgkmcnt(0)
	v_mfma_f32_16x16x32_bf16 v[62:65], v[130:133], v[194:197], v[62:65]
	v_mfma_f32_16x16x32_bf16 v[58:61], v[138:141], v[194:197], v[58:61]
	v_mfma_f32_16x16x32_bf16 v[54:57], v[130:133], v[202:205], v[54:57]
	v_mfma_f32_16x16x32_bf16 v[46:49], v[138:141], v[202:205], v[46:49]
	v_mfma_f32_16x16x32_bf16 v[38:41], v[130:133], v[218:221], v[38:41]
	v_mfma_f32_16x16x32_bf16 v[30:33], v[138:141], v[218:221], v[30:33]
	v_mfma_f32_16x16x32_bf16 v[22:25], v[130:133], v[226:229], v[22:25]
	v_mfma_f32_16x16x32_bf16 v[14:17], v[138:141], v[226:229], v[14:17]
	v_mfma_f32_16x16x32_bf16 v[62:65], v[134:137], v[198:201], v[62:65]
	v_mfma_f32_16x16x32_bf16 v[58:61], v[142:145], v[198:201], v[58:61]
	v_mfma_f32_16x16x32_bf16 v[54:57], v[134:137], v[206:209], v[54:57]
	v_mfma_f32_16x16x32_bf16 v[46:49], v[142:145], v[206:209], v[46:49]
	v_mfma_f32_16x16x32_bf16 v[38:41], v[134:137], v[222:225], v[38:41]
	v_mfma_f32_16x16x32_bf16 v[30:33], v[142:145], v[222:225], v[30:33]
	v_mfma_f32_16x16x32_bf16 v[22:25], v[134:137], v[230:233], v[22:25]
	v_mfma_f32_16x16x32_bf16 v[14:17], v[142:145], v[230:233], v[14:17]
	s_setprio 0
	s_setprio 1
	v_mfma_f32_16x16x32_bf16 v[50:53], v[162:165], v[194:197], v[50:53]
	v_mfma_f32_16x16x32_bf16 v[42:45], v[170:173], v[194:197], v[42:45]
	v_mfma_f32_16x16x32_bf16 v[34:37], v[162:165], v[202:205], v[34:37]
	v_mfma_f32_16x16x32_bf16 v[26:29], v[170:173], v[202:205], v[26:29]
	v_mfma_f32_16x16x32_bf16 v[18:21], v[162:165], v[218:221], v[18:21]
	v_mfma_f32_16x16x32_bf16 v[10:13], v[170:173], v[218:221], v[10:13]
	v_mfma_f32_16x16x32_bf16 v[6:9], v[162:165], v[226:229], v[6:9]
	v_mfma_f32_16x16x32_bf16 v[2:5], v[170:173], v[226:229], v[2:5]
	v_mfma_f32_16x16x32_bf16 v[50:53], v[166:169], v[198:201], v[50:53]
	v_mfma_f32_16x16x32_bf16 v[42:45], v[190:193], v[198:201], v[42:45]
	v_mfma_f32_16x16x32_bf16 v[34:37], v[166:169], v[206:209], v[34:37]
	v_mfma_f32_16x16x32_bf16 v[26:29], v[190:193], v[206:209], v[26:29]
	v_mfma_f32_16x16x32_bf16 v[18:21], v[166:169], v[222:225], v[18:21]
	v_mfma_f32_16x16x32_bf16 v[10:13], v[190:193], v[222:225], v[10:13]
	v_mfma_f32_16x16x32_bf16 v[6:9], v[166:169], v[230:233], v[6:9]
	v_mfma_f32_16x16x32_bf16 v[2:5], v[190:193], v[230:233], v[2:5]
	s_setprio 0
	s_barrier
	s_add_i32 s78, s78, 2
	s_add_u32 s18, s18, 0x100
	s_addc_u32 s19, s19, 0
	s_add_u32 s69, s69, 0x100
	s_addc_u32 s71, s71, 0
	s_cmp_gt_u32 s78, 13
